# v12 + accumulator zero-fill between units with v_mov_b64 (half the VALU instructions in the unit transition)
# baseline (speedup 1.0000x reference)
.LBB0_640:
	s_lshl_b32 s65, s64, 21
	s_andn2_b64 vcc, exec, s[40:41]
	s_lshl_b32 s66, s63, 21
	s_cbranch_vccnz .LBB0_648
	s_and_b64 s[18:19], s[4:5], exec
	v_mov_b32_e32 v2, 0
	s_cselect_b32 s69, s65, s71
	s_cselect_b32 s70, s66, s72
	s_add_i32 s71, s71, 0x180080
	s_addk_i32 s72, 0x100
	s_mov_b32 s73, 0
	v_mov_b32_e32 v3, v2
	v_mov_b64_e32 v[4:5], 0
	s_waitcnt vmcnt(35)
	v_mov_b64_e32 v[10:11], 0
	v_mov_b64_e32 v[12:13], 0
	s_waitcnt vmcnt(33)
	v_mov_b64_e32 v[18:19], 0
	v_mov_b64_e32 v[20:21], 0
	s_waitcnt vmcnt(31)
	v_mov_b64_e32 v[26:27], 0
	v_mov_b64_e32 v[28:29], 0
	s_waitcnt vmcnt(29)
	v_mov_b64_e32 v[34:35], 0
	v_mov_b64_e32 v[36:37], 0
	s_waitcnt vmcnt(27)
	v_mov_b64_e32 v[42:43], 0
	v_mov_b64_e32 v[44:45], 0
	s_waitcnt vmcnt(25)
	v_mov_b64_e32 v[50:51], 0
	v_mov_b64_e32 v[52:53], 0
	s_waitcnt vmcnt(23)
	v_mov_b64_e32 v[58:59], 0
	v_mov_b64_e32 v[60:61], 0
	v_mov_b64_e32 v[6:7], 0
	v_mov_b64_e32 v[8:9], 0
	v_mov_b64_e32 v[14:15], 0
	v_mov_b64_e32 v[16:17], 0
	v_mov_b64_e32 v[22:23], 0
	v_mov_b64_e32 v[24:25], 0
	v_mov_b64_e32 v[30:31], 0
	v_mov_b64_e32 v[32:33], 0
	v_mov_b64_e32 v[38:39], 0
	v_mov_b64_e32 v[40:41], 0
	v_mov_b64_e32 v[46:47], 0
	v_mov_b64_e32 v[48:49], 0
	v_mov_b64_e32 v[54:55], 0
	v_mov_b64_e32 v[56:57], 0
	s_waitcnt vmcnt(22)
	v_mov_b64_e32 v[62:63], 0
	v_mov_b64_e32 v[64:65], 0
	v_mov_b64_e32 v[70:71], 0
	v_mov_b64_e32 v[72:73], 0
	v_mov_b64_e32 v[74:75], 0
	v_mov_b64_e32 v[76:77], 0
	v_mov_b64_e32 v[82:83], 0
	v_mov_b64_e32 v[84:85], 0
	v_mov_b64_e32 v[90:91], 0
	v_mov_b64_e32 v[92:93], 0
	v_mov_b64_e32 v[98:99], 0
	v_mov_b64_e32 v[100:101], 0
	v_mov_b64_e32 v[106:107], 0
	v_mov_b64_e32 v[108:109], 0
	v_mov_b64_e32 v[122:123], 0
	v_mov_b64_e32 v[124:125], 0
	v_mov_b64_e32 v[126:127], 0
	v_mov_b64_e32 v[128:129], 0
	v_mov_b64_e32 v[66:67], 0
	v_mov_b64_e32 v[68:69], 0
	v_mov_b64_e32 v[78:79], 0
	v_mov_b64_e32 v[80:81], 0
	v_mov_b64_e32 v[86:87], 0
	v_mov_b64_e32 v[88:89], 0
	v_mov_b64_e32 v[94:95], 0
	v_mov_b64_e32 v[96:97], 0
	v_mov_b64_e32 v[102:103], 0
	v_mov_b64_e32 v[104:105], 0
	v_mov_b64_e32 v[110:111], 0
	v_mov_b64_e32 v[112:113], 0
	v_mov_b64_e32 v[114:115], 0
	v_mov_b64_e32 v[116:117], 0
	v_mov_b64_e32 v[118:119], 0
	v_mov_b64_e32 v[120:121], 0

.LBB0_797:
	s_mul_i32 s73, s72, 0x560000
	s_andn2_b64 vcc, exec, s[36:37]
	s_mul_i32 s74, s71, 0x560000
	s_cbranch_vccnz .LBB0_823
	s_and_b64 s[6:7], s[4:5], exec
	v_mov_b32_e32 v2, 0
	s_cselect_b32 s6, s73, s77
	s_cselect_b32 s7, s74, s78
	s_add_i32 s77, s77, 0x408080
	s_addk_i32 s78, 0x100
	s_mov_b32 s79, 0
	s_waitcnt lgkmcnt(0)
	v_mov_b32_e32 v3, v2
	v_mov_b64_e32 v[4:5], 0
	v_mov_b64_e32 v[6:7], 0
	v_mov_b64_e32 v[8:9], 0
	s_waitcnt vmcnt(35)
	v_mov_b64_e32 v[10:11], 0
	v_mov_b64_e32 v[12:13], 0
	s_waitcnt vmcnt(34)
	v_mov_b64_e32 v[14:15], 0
	v_mov_b64_e32 v[16:17], 0
	s_waitcnt vmcnt(32)
	v_mov_b64_e32 v[22:23], 0
	v_mov_b64_e32 v[24:25], 0
	s_waitcnt vmcnt(30)
	v_mov_b64_e32 v[30:31], 0
	v_mov_b64_e32 v[32:33], 0
	s_waitcnt vmcnt(28)
	v_mov_b64_e32 v[38:39], 0
	v_mov_b64_e32 v[40:41], 0
	s_waitcnt vmcnt(26)
	v_mov_b64_e32 v[46:47], 0
	v_mov_b64_e32 v[48:49], 0
	v_mov_b64_e32 v[18:19], 0
	v_mov_b64_e32 v[20:21], 0
	v_mov_b64_e32 v[26:27], 0
	v_mov_b64_e32 v[28:29], 0
	v_mov_b64_e32 v[34:35], 0
	v_mov_b64_e32 v[36:37], 0
	v_mov_b64_e32 v[42:43], 0
	v_mov_b64_e32 v[44:45], 0
	s_waitcnt vmcnt(25)
	v_mov_b64_e32 v[50:51], 0
	v_mov_b64_e32 v[52:53], 0
	s_waitcnt vmcnt(24)
	v_mov_b64_e32 v[54:55], 0
	v_mov_b64_e32 v[56:57], 0
	s_waitcnt vmcnt(23)
	v_mov_b64_e32 v[58:59], 0
	v_mov_b64_e32 v[60:61], 0
	s_waitcnt vmcnt(22)
	v_mov_b64_e32 v[62:63], 0
	v_mov_b64_e32 v[64:65], 0
	v_mov_b64_e32 v[66:67], 0
	v_mov_b64_e32 v[68:69], 0
	v_mov_b64_e32 v[70:71], 0
	v_mov_b64_e32 v[72:73], 0
	v_mov_b64_e32 v[74:75], 0
	v_mov_b64_e32 v[76:77], 0
	v_mov_b64_e32 v[78:79], 0
	v_mov_b64_e32 v[80:81], 0
	v_mov_b64_e32 v[86:87], 0
	v_mov_b64_e32 v[88:89], 0
	v_mov_b64_e32 v[94:95], 0
	v_mov_b64_e32 v[96:97], 0
	v_mov_b64_e32 v[102:103], 0
	v_mov_b64_e32 v[104:105], 0
	v_mov_b64_e32 v[110:111], 0
	v_mov_b64_e32 v[112:113], 0
	v_mov_b64_e32 v[82:83], 0
	v_mov_b64_e32 v[84:85], 0
	v_mov_b64_e32 v[90:91], 0
	v_mov_b64_e32 v[92:93], 0
	v_mov_b64_e32 v[98:99], 0
	v_mov_b64_e32 v[100:101], 0
	v_mov_b64_e32 v[106:107], 0
	v_mov_b64_e32 v[108:109], 0
	v_mov_b64_e32 v[114:115], 0
	v_mov_b64_e32 v[116:117], 0
	v_mov_b64_e32 v[118:119], 0
	v_mov_b64_e32 v[120:121], 0
	v_mov_b64_e32 v[122:123], 0
	v_mov_b64_e32 v[124:125], 0
	v_mov_b64_e32 v[126:127], 0
	v_mov_b64_e32 v[128:129], 0

.LBB0_890:
	s_lshl_b32 s85, s31, 21
	s_andn2_b64 vcc, exec, s[46:47]
	s_lshl_b32 s86, s30, 21
	s_cbranch_vccnz .LBB0_940
	s_and_b64 s[6:7], s[4:5], exec
	v_mov_b32_e32 v2, 0
	s_cselect_b32 s6, s85, s8
	s_cselect_b32 s7, s86, s9
	s_add_i32 s8, s8, 0x180080
	s_addk_i32 s9, 0x100
	s_mov_b32 s52, 0
	v_mov_b32_e32 v3, v2
	v_mov_b64_e32 v[4:5], 0
	s_waitcnt vmcnt(35)
	v_mov_b64_e32 v[10:11], 0
	v_mov_b64_e32 v[12:13], 0
	s_waitcnt vmcnt(33)
	v_mov_b64_e32 v[18:19], 0
	v_mov_b64_e32 v[20:21], 0
	s_waitcnt vmcnt(31)
	v_mov_b64_e32 v[26:27], 0
	v_mov_b64_e32 v[28:29], 0
	s_waitcnt vmcnt(29)
	v_mov_b64_e32 v[34:35], 0
	v_mov_b64_e32 v[36:37], 0
	s_waitcnt vmcnt(27)
	v_mov_b64_e32 v[42:43], 0
	v_mov_b64_e32 v[44:45], 0
	s_waitcnt vmcnt(25)
	v_mov_b64_e32 v[50:51], 0
	v_mov_b64_e32 v[52:53], 0
	s_waitcnt vmcnt(23)
	v_mov_b64_e32 v[58:59], 0
	v_mov_b64_e32 v[60:61], 0
	v_mov_b64_e32 v[6:7], 0
	v_mov_b64_e32 v[8:9], 0
	v_mov_b64_e32 v[14:15], 0
	v_mov_b64_e32 v[16:17], 0
	v_mov_b64_e32 v[22:23], 0
	v_mov_b64_e32 v[24:25], 0
	v_mov_b64_e32 v[30:31], 0
	v_mov_b64_e32 v[32:33], 0
	v_mov_b64_e32 v[38:39], 0
	v_mov_b64_e32 v[40:41], 0
	v_mov_b64_e32 v[46:47], 0
	v_mov_b64_e32 v[48:49], 0
	v_mov_b64_e32 v[54:55], 0
	v_mov_b64_e32 v[56:57], 0
	s_waitcnt vmcnt(22)
	v_mov_b64_e32 v[62:63], 0
	v_mov_b64_e32 v[64:65], 0
	v_mov_b64_e32 v[66:67], 0
	v_mov_b64_e32 v[68:69], 0
	v_mov_b64_e32 v[74:75], 0
	v_mov_b64_e32 v[76:77], 0
	v_mov_b64_e32 v[82:83], 0
	v_mov_b64_e32 v[84:85], 0
	v_mov_b64_e32 v[86:87], 0
	v_mov_b64_e32 v[88:89], 0
	v_mov_b64_e32 v[98:99], 0
	v_mov_b64_e32 v[100:101], 0
	v_mov_b64_e32 v[106:107], 0
	v_mov_b64_e32 v[108:109], 0
	v_mov_b64_e32 v[114:115], 0
	v_mov_b64_e32 v[116:117], 0
	v_mov_b64_e32 v[122:123], 0
	v_mov_b64_e32 v[124:125], 0
	v_mov_b64_e32 v[70:71], 0
	v_mov_b64_e32 v[72:73], 0
	v_mov_b64_e32 v[78:79], 0
	v_mov_b64_e32 v[80:81], 0
	v_mov_b64_e32 v[90:91], 0
	v_mov_b64_e32 v[92:93], 0
	v_mov_b64_e32 v[94:95], 0
	v_mov_b64_e32 v[96:97], 0
	v_mov_b64_e32 v[102:103], 0
	v_mov_b64_e32 v[104:105], 0
	v_mov_b64_e32 v[110:111], 0
	v_mov_b64_e32 v[112:113], 0
	v_mov_b64_e32 v[118:119], 0
	v_mov_b64_e32 v[120:121], 0
	v_mov_b64_e32 v[126:127], 0
	v_mov_b64_e32 v[128:129], 0

.LBB0_1018:
	s_add_i32 s6, s84, s86
	s_andn2_b64 vcc, exec, s[52:53]
	s_lshl_b32 s85, s6, 18
	s_cbranch_vccnz .LBB0_1026
	s_and_b64 s[6:7], s[56:57], exec
	v_mov_b32_e32 v2, 0
	s_cselect_b32 s87, s85, s88
	s_addk_i32 s88, 0x100
	s_mov_b32 s6, 0
	s_mov_b32 s89, 0
	v_mov_b32_e32 v3, v2
	v_mov_b64_e32 v[4:5], 0
	v_mov_b64_e32 v[6:7], 0
	v_mov_b64_e32 v[8:9], 0
	v_mov_b64_e32 v[18:19], 0
	v_mov_b64_e32 v[20:21], 0
	v_mov_b64_e32 v[22:23], 0
	v_mov_b64_e32 v[24:25], 0
	v_mov_b64_e32 v[34:35], 0
	v_mov_b64_e32 v[36:37], 0
	v_mov_b64_e32 v[38:39], 0
	v_mov_b64_e32 v[40:41], 0
	v_mov_b64_e32 v[50:51], 0
	v_mov_b64_e32 v[52:53], 0
	v_mov_b64_e32 v[54:55], 0
	v_mov_b64_e32 v[56:57], 0
	v_mov_b64_e32 v[10:11], 0
	v_mov_b64_e32 v[12:13], 0
	v_mov_b64_e32 v[14:15], 0
	v_mov_b64_e32 v[16:17], 0
	v_mov_b64_e32 v[26:27], 0
	v_mov_b64_e32 v[28:29], 0
	v_mov_b64_e32 v[30:31], 0
	v_mov_b64_e32 v[32:33], 0
	v_mov_b64_e32 v[42:43], 0
	v_mov_b64_e32 v[44:45], 0
	v_mov_b64_e32 v[46:47], 0
	v_mov_b64_e32 v[48:49], 0
	v_mov_b64_e32 v[58:59], 0
	v_mov_b64_e32 v[60:61], 0
	v_mov_b64_e32 v[62:63], 0
	v_mov_b64_e32 v[64:65], 0
	v_mov_b64_e32 v[66:67], 0
	v_mov_b64_e32 v[68:69], 0
	v_mov_b64_e32 v[70:71], 0
	v_mov_b64_e32 v[72:73], 0
	v_mov_b64_e32 v[82:83], 0
	v_mov_b64_e32 v[84:85], 0
	v_mov_b64_e32 v[86:87], 0
	v_mov_b64_e32 v[88:89], 0
	v_mov_b64_e32 v[98:99], 0
	v_mov_b64_e32 v[100:101], 0
	v_mov_b64_e32 v[102:103], 0
	v_mov_b64_e32 v[104:105], 0
	v_mov_b64_e32 v[114:115], 0
	v_mov_b64_e32 v[116:117], 0
	v_mov_b64_e32 v[118:119], 0
	v_mov_b64_e32 v[120:121], 0
	v_mov_b64_e32 v[74:75], 0
	v_mov_b64_e32 v[76:77], 0
	v_mov_b64_e32 v[78:79], 0
	v_mov_b64_e32 v[80:81], 0
	v_mov_b64_e32 v[90:91], 0
	v_mov_b64_e32 v[92:93], 0
	v_mov_b64_e32 v[94:95], 0
	v_mov_b64_e32 v[96:97], 0
	v_mov_b64_e32 v[106:107], 0
	v_mov_b64_e32 v[108:109], 0
	v_mov_b64_e32 v[110:111], 0
	v_mov_b64_e32 v[112:113], 0
	v_mov_b64_e32 v[122:123], 0
	v_mov_b64_e32 v[124:125], 0
	v_mov_b64_e32 v[126:127], 0
	v_mov_b64_e32 v[128:129], 0

.LBB0_1033:
	s_add_i32 s58, s58, 1
	s_lshr_b32 s40, s58, 1
	s_mul_i32 s40, s40, s33
	s_add_i32 s62, s40, s2
	s_cmpk_lt_i32 s62, 0x200
	s_cselect_b64 s[40:41], -1, 0
	s_ashr_i32 s59, s62, 6
	s_and_b32 s63, s58, 1
	s_and_b32 s61, s62, 63
	s_lshl_b32 s64, s59, 23
	s_lshl_b32 s69, s63, 26
	s_mul_i32 s62, s62, 0x60000
	s_lshl_b32 s68, s61, 9
	s_add_i32 s64, s64, s69
	s_bitset1_b32 s62, 10
	s_or_b32 s64, s64, s68
	s_and_b64 vcc, exec, s[4:5]
	v_mov_b32_e32 v129, 0
	v_mov_b32_e32 v128, 0
	v_mov_b32_e32 v127, 0
	v_mov_b32_e32 v126, 0
	v_mov_b32_e32 v125, 0
	v_mov_b32_e32 v124, 0
	v_mov_b32_e32 v123, 0
	v_mov_b32_e32 v122, 0
	v_mov_b32_e32 v113, 0
	v_mov_b32_e32 v112, 0
	v_mov_b32_e32 v111, 0
	v_mov_b32_e32 v110, 0
	v_mov_b32_e32 v109, 0
	v_mov_b32_e32 v108, 0
	v_mov_b32_e32 v107, 0
	v_mov_b32_e32 v106, 0
	v_mov_b32_e32 v97, 0
	v_mov_b32_e32 v96, 0
	v_mov_b32_e32 v95, 0
	v_mov_b32_e32 v94, 0
	v_mov_b32_e32 v93, 0
	v_mov_b32_e32 v92, 0
	v_mov_b32_e32 v91, 0
	v_mov_b32_e32 v90, 0
	v_mov_b32_e32 v81, 0
	v_mov_b32_e32 v80, 0
	v_mov_b32_e32 v79, 0
	v_mov_b32_e32 v78, 0
	v_mov_b32_e32 v77, 0
	v_mov_b32_e32 v76, 0
	v_mov_b32_e32 v75, 0
	v_mov_b32_e32 v74, 0
	v_mov_b32_e32 v121, 0
	v_mov_b32_e32 v120, 0
	v_mov_b32_e32 v119, 0
	v_mov_b32_e32 v118, 0
	v_mov_b32_e32 v117, 0
	v_mov_b32_e32 v116, 0
	v_mov_b32_e32 v115, 0
	v_mov_b32_e32 v114, 0
	v_mov_b32_e32 v105, 0
	v_mov_b32_e32 v104, 0
	v_mov_b32_e32 v103, 0
	v_mov_b32_e32 v102, 0
	v_mov_b32_e32 v101, 0
	v_mov_b32_e32 v100, 0
	v_mov_b32_e32 v99, 0
	v_mov_b32_e32 v98, 0
	v_mov_b32_e32 v89, 0
	v_mov_b32_e32 v88, 0
	v_mov_b32_e32 v87, 0
	v_mov_b32_e32 v86, 0
	v_mov_b32_e32 v85, 0
	v_mov_b32_e32 v84, 0
	v_mov_b32_e32 v83, 0
	v_mov_b32_e32 v82, 0
	v_mov_b32_e32 v73, 0
	v_mov_b32_e32 v72, 0
	v_mov_b32_e32 v71, 0
	v_mov_b32_e32 v70, 0
	v_mov_b32_e32 v69, 0
	v_mov_b32_e32 v68, 0
	v_mov_b32_e32 v67, 0
	v_mov_b32_e32 v66, 0
	v_mov_b32_e32 v65, 0
	v_mov_b32_e32 v64, 0
	v_mov_b32_e32 v63, 0
	v_mov_b32_e32 v62, 0
	v_mov_b32_e32 v61, 0
	v_mov_b32_e32 v60, 0
	v_mov_b32_e32 v59, 0
	v_mov_b32_e32 v58, 0
	v_mov_b32_e32 v49, 0
	v_mov_b32_e32 v48, 0
	v_mov_b32_e32 v47, 0
	v_mov_b32_e32 v46, 0
	v_mov_b32_e32 v45, 0
	v_mov_b32_e32 v44, 0
	v_mov_b32_e32 v43, 0
	v_mov_b32_e32 v42, 0
	v_mov_b32_e32 v33, 0
	v_mov_b32_e32 v32, 0
	v_mov_b32_e32 v31, 0
	v_mov_b32_e32 v30, 0
	v_mov_b32_e32 v29, 0
	v_mov_b32_e32 v28, 0
	v_mov_b32_e32 v27, 0
	v_mov_b32_e32 v26, 0
	v_mov_b32_e32 v17, 0
	v_mov_b32_e32 v16, 0
	v_mov_b32_e32 v15, 0
	v_mov_b32_e32 v14, 0
	v_mov_b32_e32 v13, 0
	v_mov_b32_e32 v12, 0
	v_mov_b32_e32 v11, 0
	v_mov_b32_e32 v10, 0
	v_mov_b32_e32 v57, 0
	v_mov_b32_e32 v56, 0
	v_mov_b32_e32 v55, 0
	v_mov_b32_e32 v54, 0
	v_mov_b32_e32 v53, 0
	v_mov_b32_e32 v52, 0
	v_mov_b32_e32 v51, 0
	v_mov_b32_e32 v50, 0
	v_mov_b32_e32 v41, 0
	v_mov_b32_e32 v40, 0
	v_mov_b32_e32 v39, 0
	v_mov_b32_e32 v38, 0
	v_mov_b32_e32 v37, 0
	v_mov_b32_e32 v36, 0
	v_mov_b32_e32 v35, 0
	v_mov_b32_e32 v34, 0
	v_mov_b32_e32 v25, 0
	v_mov_b32_e32 v24, 0
	v_mov_b32_e32 v23, 0
	v_mov_b32_e32 v22, 0
	v_mov_b32_e32 v21, 0
	v_mov_b32_e32 v20, 0
	v_mov_b32_e32 v19, 0
	v_mov_b32_e32 v18, 0
	v_mov_b32_e32 v9, 0
	v_mov_b32_e32 v8, 0
	v_mov_b32_e32 v7, 0
	v_mov_b32_e32 v6, 0
	v_mov_b32_e32 v5, 0
	v_mov_b32_e32 v4, 0
	v_mov_b32_e32 v3, 0
	v_mov_b32_e32 v2, 0
	s_cbranch_vccnz .LBB0_1036
	s_and_b64 s[68:69], s[40:41], exec
	v_mov_b32_e32 v2, 0
	s_cselect_b32 s68, s62, s70
	s_cselect_b32 s69, s64, s71
	s_add_i32 s70, s70, 0x48080
	s_addk_i32 s71, 0x100
	s_mov_b32 s72, 0
	v_mov_b32_e32 v3, v2
	v_mov_b64_e32 v[4:5], 0
	v_mov_b64_e32 v[6:7], 0
	v_mov_b64_e32 v[8:9], 0
	v_mov_b64_e32 v[18:19], 0
	v_mov_b64_e32 v[20:21], 0
	v_mov_b64_e32 v[22:23], 0
	v_mov_b64_e32 v[24:25], 0
	v_mov_b64_e32 v[34:35], 0
	v_mov_b64_e32 v[36:37], 0
	v_mov_b64_e32 v[38:39], 0
	v_mov_b64_e32 v[40:41], 0
	v_mov_b64_e32 v[50:51], 0
	v_mov_b64_e32 v[52:53], 0
	v_mov_b64_e32 v[54:55], 0
	v_mov_b64_e32 v[56:57], 0
	v_mov_b64_e32 v[10:11], 0
	v_mov_b64_e32 v[12:13], 0
	v_mov_b64_e32 v[14:15], 0
	v_mov_b64_e32 v[16:17], 0
	v_mov_b64_e32 v[26:27], 0
	v_mov_b64_e32 v[28:29], 0
	v_mov_b64_e32 v[30:31], 0
	v_mov_b64_e32 v[32:33], 0
	v_mov_b64_e32 v[42:43], 0
	v_mov_b64_e32 v[44:45], 0
	v_mov_b64_e32 v[46:47], 0
	v_mov_b64_e32 v[48:49], 0
	v_mov_b64_e32 v[58:59], 0
	v_mov_b64_e32 v[60:61], 0
	v_mov_b64_e32 v[62:63], 0
	v_mov_b64_e32 v[64:65], 0
	v_mov_b64_e32 v[66:67], 0
	v_mov_b64_e32 v[68:69], 0
	v_mov_b64_e32 v[70:71], 0
	v_mov_b64_e32 v[72:73], 0
	v_mov_b64_e32 v[82:83], 0
	v_mov_b64_e32 v[84:85], 0
	v_mov_b64_e32 v[86:87], 0
	v_mov_b64_e32 v[88:89], 0
	v_mov_b64_e32 v[98:99], 0
	v_mov_b64_e32 v[100:101], 0
	v_mov_b64_e32 v[102:103], 0
	v_mov_b64_e32 v[104:105], 0
	v_mov_b64_e32 v[114:115], 0
	v_mov_b64_e32 v[116:117], 0
	v_mov_b64_e32 v[118:119], 0
	v_mov_b64_e32 v[120:121], 0
	v_mov_b64_e32 v[74:75], 0
	v_mov_b64_e32 v[76:77], 0
	v_mov_b64_e32 v[78:79], 0
	v_mov_b64_e32 v[80:81], 0
	v_mov_b64_e32 v[90:91], 0
	v_mov_b64_e32 v[92:93], 0
	v_mov_b64_e32 v[94:95], 0
	v_mov_b64_e32 v[96:97], 0
	v_mov_b64_e32 v[106:107], 0
	v_mov_b64_e32 v[108:109], 0
	v_mov_b64_e32 v[110:111], 0
	v_mov_b64_e32 v[112:113], 0
	v_mov_b64_e32 v[122:123], 0
	v_mov_b64_e32 v[124:125], 0
	v_mov_b64_e32 v[126:127], 0
	v_mov_b64_e32 v[128:129], 0

.LBB0_1048:
	s_add_i32 s41, s41, 1
	s_mul_i32 s18, s41, s33
	s_add_i32 s18, s18, s2
	s_mov_b32 s35, s58
	s_mov_b32 s59, s57
	s_ashr_i32 s57, s18, 6
	s_and_b32 s58, s18, 63
	s_cmpk_lt_i32 s18, 0x200
	s_cselect_b64 s[36:37], -1, 0
	s_and_b64 s[18:19], s[36:37], exec
	s_cselect_b32 s18, s57, s59
	s_cselect_b32 s19, s58, s35
	s_lshl_b32 s59, s18, 9
	s_lshl_b32 s18, s19, 20
	s_add_i32 s59, s59, s18
	s_and_b64 vcc, exec, s[4:5]
	v_mov_b32_e32 v129, 0
	v_mov_b32_e32 v128, 0
	v_mov_b32_e32 v127, 0
	v_mov_b32_e32 v126, 0
	v_mov_b32_e32 v125, 0
	v_mov_b32_e32 v124, 0
	v_mov_b32_e32 v123, 0
	v_mov_b32_e32 v122, 0
	v_mov_b32_e32 v113, 0
	v_mov_b32_e32 v112, 0
	v_mov_b32_e32 v111, 0
	v_mov_b32_e32 v110, 0
	v_mov_b32_e32 v109, 0
	v_mov_b32_e32 v108, 0
	v_mov_b32_e32 v107, 0
	v_mov_b32_e32 v106, 0
	v_mov_b32_e32 v97, 0
	s_waitcnt vmcnt(24)
	v_mov_b32_e32 v96, 0
	v_mov_b32_e32 v95, 0
	v_mov_b32_e32 v94, 0
	v_mov_b32_e32 v93, 0
	v_mov_b32_e32 v92, 0
	v_mov_b32_e32 v91, 0
	v_mov_b32_e32 v90, 0
	v_mov_b32_e32 v81, 0
	v_mov_b32_e32 v80, 0
	v_mov_b32_e32 v79, 0
	v_mov_b32_e32 v78, 0
	v_mov_b32_e32 v77, 0
	v_mov_b32_e32 v76, 0
	v_mov_b32_e32 v75, 0
	v_mov_b32_e32 v74, 0
	v_mov_b32_e32 v121, 0
	v_mov_b32_e32 v120, 0
	v_mov_b32_e32 v119, 0
	v_mov_b32_e32 v118, 0
	v_mov_b32_e32 v117, 0
	v_mov_b32_e32 v116, 0
	v_mov_b32_e32 v115, 0
	v_mov_b32_e32 v114, 0
	v_mov_b32_e32 v105, 0
	v_mov_b32_e32 v104, 0
	v_mov_b32_e32 v103, 0
	s_waitcnt vmcnt(23)
	v_mov_b32_e32 v102, 0
	v_mov_b32_e32 v101, 0
	s_waitcnt vmcnt(22)
	v_mov_b32_e32 v100, 0
	v_mov_b32_e32 v99, 0
	v_mov_b32_e32 v98, 0
	v_mov_b32_e32 v89, 0
	v_mov_b32_e32 v88, 0
	v_mov_b32_e32 v87, 0
	v_mov_b32_e32 v86, 0
	v_mov_b32_e32 v85, 0
	v_mov_b32_e32 v84, 0
	v_mov_b32_e32 v83, 0
	v_mov_b32_e32 v82, 0
	v_mov_b32_e32 v73, 0
	v_mov_b32_e32 v72, 0
	v_mov_b32_e32 v71, 0
	v_mov_b32_e32 v70, 0
	v_mov_b32_e32 v69, 0
	v_mov_b32_e32 v68, 0
	v_mov_b32_e32 v67, 0
	v_mov_b32_e32 v66, 0
	v_mov_b32_e32 v65, 0
	v_mov_b32_e32 v64, 0
	v_mov_b32_e32 v63, 0
	v_mov_b32_e32 v62, 0
	v_mov_b32_e32 v61, 0
	v_mov_b32_e32 v60, 0
	v_mov_b32_e32 v59, 0
	v_mov_b32_e32 v58, 0
	v_mov_b32_e32 v49, 0
	v_mov_b32_e32 v48, 0
	v_mov_b32_e32 v47, 0
	v_mov_b32_e32 v46, 0
	v_mov_b32_e32 v45, 0
	v_mov_b32_e32 v44, 0
	v_mov_b32_e32 v43, 0
	v_mov_b32_e32 v42, 0
	v_mov_b32_e32 v33, 0
	v_mov_b32_e32 v32, 0
	v_mov_b32_e32 v31, 0
	v_mov_b32_e32 v30, 0
	v_mov_b32_e32 v29, 0
	v_mov_b32_e32 v28, 0
	v_mov_b32_e32 v27, 0
	v_mov_b32_e32 v26, 0
	v_mov_b32_e32 v17, 0
	v_mov_b32_e32 v16, 0
	v_mov_b32_e32 v15, 0
	v_mov_b32_e32 v14, 0
	v_mov_b32_e32 v13, 0
	v_mov_b32_e32 v12, 0
	v_mov_b32_e32 v11, 0
	v_mov_b32_e32 v10, 0
	v_mov_b32_e32 v57, 0
	v_mov_b32_e32 v56, 0
	v_mov_b32_e32 v55, 0
	v_mov_b32_e32 v54, 0
	v_mov_b32_e32 v53, 0
	v_mov_b32_e32 v52, 0
	v_mov_b32_e32 v51, 0
	v_mov_b32_e32 v50, 0
	v_mov_b32_e32 v41, 0
	v_mov_b32_e32 v40, 0
	v_mov_b32_e32 v39, 0
	v_mov_b32_e32 v38, 0
	v_mov_b32_e32 v37, 0
	v_mov_b32_e32 v36, 0
	v_mov_b32_e32 v35, 0
	v_mov_b32_e32 v34, 0
	v_mov_b32_e32 v25, 0
	v_mov_b32_e32 v24, 0
	v_mov_b32_e32 v23, 0
	v_mov_b32_e32 v22, 0
	v_mov_b32_e32 v21, 0
	v_mov_b32_e32 v20, 0
	v_mov_b32_e32 v19, 0
	v_mov_b32_e32 v18, 0
	v_mov_b32_e32 v9, 0
	v_mov_b32_e32 v8, 0
	v_mov_b32_e32 v7, 0
	v_mov_b32_e32 v6, 0
	v_mov_b32_e32 v5, 0
	v_mov_b32_e32 v4, 0
	v_mov_b32_e32 v3, 0
	v_mov_b32_e32 v2, 0
	s_cbranch_vccnz .LBB0_1051
	s_and_b64 s[18:19], s[36:37], exec
	v_mov_b32_e32 v2, 0
	s_cselect_b32 s35, s59, s61
	s_add_i32 s61, s61, 0xc0080
	s_mov_b32 s62, 0
	v_mov_b32_e32 v3, v2
	v_mov_b64_e32 v[4:5], 0
	v_mov_b64_e32 v[6:7], 0
	v_mov_b64_e32 v[8:9], 0
	v_mov_b64_e32 v[18:19], 0
	v_mov_b64_e32 v[20:21], 0
	v_mov_b64_e32 v[22:23], 0
	v_mov_b64_e32 v[24:25], 0
	v_mov_b64_e32 v[34:35], 0
	v_mov_b64_e32 v[36:37], 0
	v_mov_b64_e32 v[38:39], 0
	v_mov_b64_e32 v[40:41], 0
	v_mov_b64_e32 v[50:51], 0
	v_mov_b64_e32 v[52:53], 0
	v_mov_b64_e32 v[54:55], 0
	v_mov_b64_e32 v[56:57], 0
	v_mov_b64_e32 v[10:11], 0
	v_mov_b64_e32 v[12:13], 0
	v_mov_b64_e32 v[14:15], 0
	v_mov_b64_e32 v[16:17], 0
	v_mov_b64_e32 v[26:27], 0
	v_mov_b64_e32 v[28:29], 0
	v_mov_b64_e32 v[30:31], 0
	v_mov_b64_e32 v[32:33], 0
	v_mov_b64_e32 v[42:43], 0
	v_mov_b64_e32 v[44:45], 0
	v_mov_b64_e32 v[46:47], 0
	v_mov_b64_e32 v[48:49], 0
	v_mov_b64_e32 v[58:59], 0
	v_mov_b64_e32 v[60:61], 0
	v_mov_b64_e32 v[62:63], 0
	v_mov_b64_e32 v[64:65], 0
	v_mov_b64_e32 v[66:67], 0
	v_mov_b64_e32 v[68:69], 0
	v_mov_b64_e32 v[70:71], 0
	v_mov_b64_e32 v[72:73], 0
	v_mov_b64_e32 v[82:83], 0
	v_mov_b64_e32 v[84:85], 0
	v_mov_b64_e32 v[86:87], 0
	v_mov_b64_e32 v[88:89], 0
	v_mov_b64_e32 v[98:99], 0
	v_mov_b64_e32 v[100:101], 0
	v_mov_b64_e32 v[102:103], 0
	v_mov_b64_e32 v[104:105], 0
	v_mov_b64_e32 v[114:115], 0
	v_mov_b64_e32 v[116:117], 0
	v_mov_b64_e32 v[118:119], 0
	v_mov_b64_e32 v[120:121], 0
	v_mov_b64_e32 v[74:75], 0
	v_mov_b64_e32 v[76:77], 0
	v_mov_b64_e32 v[78:79], 0
	v_mov_b64_e32 v[80:81], 0
	v_mov_b64_e32 v[90:91], 0
	v_mov_b64_e32 v[92:93], 0
	v_mov_b64_e32 v[94:95], 0
	v_mov_b64_e32 v[96:97], 0
	v_mov_b64_e32 v[106:107], 0
	v_mov_b64_e32 v[108:109], 0
	v_mov_b64_e32 v[110:111], 0
	v_mov_b64_e32 v[112:113], 0
	v_mov_b64_e32 v[122:123], 0
	v_mov_b64_e32 v[124:125], 0
	v_mov_b64_e32 v[126:127], 0
	v_mov_b64_e32 v[128:129], 0

.LBB0_1114:
	v_ashrrev_i32_e32 v2, 16, v146
	s_waitcnt vmcnt(22)
	v_bfe_u32 v6, v146, 13, 3
	v_lshl_or_b32 v4, v2, 3, v6
	v_ashrrev_i32_e32 v5, 31, v4
	v_lshl_add_u64 v[4:5], v[4:5], 2, s[16:17]
	global_load_dword v4, v[4:5], off
	v_bfe_u32 v5, v146, 5, 8
	v_lshl_or_b32 v5, v6, 14, v5
	v_mul_i32_i24_e32 v6, 0xffffff00, v2
	v_mul_u32_u24_e32 v2, 0x300, v5
	v_lshlrev_b32_e32 v2, 1, v2
	s_waitcnt vmcnt(20)
	v_lshlrev_b32_e32 v18, 4, v146
	v_ashrrev_i32_e32 v7, 31, v6
	v_lshl_add_u64 v[16:17], s[8:9], 0, v[2:3]
	v_and_b32_e32 v2, 0x1f0, v18
	v_lshl_add_u64 v[6:7], v[6:7], 1, v[16:17]
	v_lshl_add_u64 v[6:7], v[6:7], 0, v[2:3]
	v_cmp_gt_u32_e32 vcc, s3, v146
	s_mov_b32 s22, 0
	s_mov_b32 s21, 63
	v_mov_b64_e32 v[8:9], 0
	v_mov_b64_e32 v[14:15], 0
	v_mov_b64_e32 v[12:13], 0
	v_mov_b64_e32 v[10:11], 0
	v_mov_b32_e32 v1, v3
	v_lshl_add_u64 v[6:7], v[6:7], 0, s[14:15]
	v_mov_b32_e32 v16, v3
	s_waitcnt vmcnt(0)
	v_mul_f32_e32 v4, 0x43800000, v4
	v_exp_f32_e32 v4, v4
	s_nop 0
	v_mov_b32_e32 v5, v4

.LBB0_1179:
	s_add_i32 s58, s58, 1
	s_mul_i32 s18, s58, s33
	s_add_i32 s84, s18, s2
	s_mov_b32 s47, s82
	s_mov_b32 s48, s81
	s_ashr_i32 s81, s84, 6
	s_and_b32 s82, s84, 63
	s_cmpk_lt_i32 s84, 0x200
	s_cselect_b64 s[44:45], -1, 0
	s_and_b64 s[18:19], s[44:45], exec
	s_cselect_b32 s18, s81, s48
	s_cselect_b32 s19, s82, s47
	s_lshl_b32 s83, s18, 9
	s_lshl_b32 s18, s19, 20
	s_add_i32 s83, s83, s18
	s_mul_i32 s84, s84, 0x60000
	s_and_b64 vcc, exec, s[4:5]
	v_mov_b32_e32 v133, 0
	v_mov_b32_e32 v132, 0
	v_mov_b32_e32 v131, 0
	v_mov_b32_e32 v130, 0
	v_mov_b32_e32 v129, 0
	v_mov_b32_e32 v128, 0
	v_mov_b32_e32 v127, 0
	v_mov_b32_e32 v126, 0
	v_mov_b32_e32 v117, 0
	v_mov_b32_e32 v116, 0
	v_mov_b32_e32 v115, 0
	v_mov_b32_e32 v114, 0
	v_mov_b32_e32 v113, 0
	v_mov_b32_e32 v112, 0
	v_mov_b32_e32 v111, 0
	v_mov_b32_e32 v110, 0
	v_mov_b32_e32 v101, 0
	s_waitcnt vmcnt(22)
	v_mov_b32_e32 v100, 0
	v_mov_b32_e32 v99, 0
	v_mov_b32_e32 v98, 0
	v_mov_b32_e32 v97, 0
	v_mov_b32_e32 v96, 0
	v_mov_b32_e32 v95, 0
	v_mov_b32_e32 v94, 0
	v_mov_b32_e32 v85, 0
	v_mov_b32_e32 v84, 0
	v_mov_b32_e32 v83, 0
	v_mov_b32_e32 v82, 0
	v_mov_b32_e32 v81, 0
	v_mov_b32_e32 v80, 0
	v_mov_b32_e32 v79, 0
	v_mov_b32_e32 v78, 0
	v_mov_b32_e32 v125, 0
	v_mov_b32_e32 v124, 0
	v_mov_b32_e32 v123, 0
	v_mov_b32_e32 v122, 0
	v_mov_b32_e32 v121, 0
	v_mov_b32_e32 v120, 0
	v_mov_b32_e32 v119, 0
	v_mov_b32_e32 v118, 0
	v_mov_b32_e32 v109, 0
	v_mov_b32_e32 v108, 0
	v_mov_b32_e32 v107, 0
	v_mov_b32_e32 v106, 0
	v_mov_b32_e32 v105, 0
	v_mov_b32_e32 v104, 0
	v_mov_b32_e32 v103, 0
	v_mov_b32_e32 v102, 0
	v_mov_b32_e32 v93, 0
	v_mov_b32_e32 v92, 0
	v_mov_b32_e32 v91, 0
	v_mov_b32_e32 v90, 0
	v_mov_b32_e32 v89, 0
	v_mov_b32_e32 v88, 0
	v_mov_b32_e32 v87, 0
	v_mov_b32_e32 v86, 0
	v_mov_b32_e32 v77, 0
	v_mov_b32_e32 v76, 0
	v_mov_b32_e32 v75, 0
	v_mov_b32_e32 v74, 0
	v_mov_b32_e32 v73, 0
	v_mov_b32_e32 v72, 0
	v_mov_b32_e32 v71, 0
	v_mov_b32_e32 v70, 0
	v_mov_b32_e32 v69, 0
	v_mov_b32_e32 v68, 0
	v_mov_b32_e32 v67, 0
	v_mov_b32_e32 v66, 0
	v_mov_b32_e32 v65, 0
	v_mov_b32_e32 v64, 0
	v_mov_b32_e32 v63, 0
	v_mov_b32_e32 v62, 0
	v_mov_b32_e32 v53, 0
	v_mov_b32_e32 v52, 0
	v_mov_b32_e32 v51, 0
	v_mov_b32_e32 v50, 0
	v_mov_b32_e32 v49, 0
	v_mov_b32_e32 v48, 0
	v_mov_b32_e32 v47, 0
	v_mov_b32_e32 v46, 0
	v_mov_b32_e32 v37, 0
	v_mov_b32_e32 v36, 0
	v_mov_b32_e32 v35, 0
	v_mov_b32_e32 v34, 0
	v_mov_b32_e32 v33, 0
	v_mov_b32_e32 v32, 0
	v_mov_b32_e32 v31, 0
	v_mov_b32_e32 v30, 0
	v_mov_b32_e32 v21, 0
	v_mov_b32_e32 v20, 0
	v_mov_b32_e32 v19, 0
	v_mov_b32_e32 v18, 0
	v_mov_b32_e32 v17, 0
	v_mov_b32_e32 v16, 0
	v_mov_b32_e32 v15, 0
	v_mov_b32_e32 v14, 0
	v_mov_b32_e32 v61, 0
	v_mov_b32_e32 v60, 0
	v_mov_b32_e32 v59, 0
	v_mov_b32_e32 v58, 0
	v_mov_b32_e32 v57, 0
	v_mov_b32_e32 v56, 0
	v_mov_b32_e32 v55, 0
	v_mov_b32_e32 v54, 0
	v_mov_b32_e32 v45, 0
	v_mov_b32_e32 v44, 0
	v_mov_b32_e32 v43, 0
	v_mov_b32_e32 v42, 0
	v_mov_b32_e32 v41, 0
	v_mov_b32_e32 v40, 0
	v_mov_b32_e32 v39, 0
	v_mov_b32_e32 v38, 0
	v_mov_b32_e32 v29, 0
	v_mov_b32_e32 v28, 0
	v_mov_b32_e32 v27, 0
	v_mov_b32_e32 v26, 0
	v_mov_b32_e32 v25, 0
	v_mov_b32_e32 v24, 0
	v_mov_b32_e32 v23, 0
	v_mov_b32_e32 v22, 0
	v_mov_b32_e32 v13, 0
	v_mov_b32_e32 v12, 0
	v_mov_b32_e32 v11, 0
	v_mov_b32_e32 v10, 0
	v_mov_b32_e32 v9, 0
	v_mov_b32_e32 v8, 0
	v_mov_b32_e32 v7, 0
	v_mov_b32_e32 v6, 0
	s_cbranch_vccnz .LBB0_1193
	s_and_b64 s[18:19], s[44:45], exec
	s_cselect_b32 s87, s83, s86
	s_cselect_b32 s88, s84, s50
	s_ashr_i32 s47, s46, 31
	s_add_i32 s89, s86, 0x80
	s_lshl_b64 s[18:19], s[46:47], 2
	v_mov_b64_e32 v[4:5], 0
	s_add_u32 s48, s60, s18
	v_mov_b32_e32 v2, v3
	v_mov_b64_e32 v[8:9], v[4:5]
	v_mov_b64_e32 v[12:13], v[4:5]
	v_mov_b64_e32 v[24:25], v[4:5]
	v_mov_b64_e32 v[28:29], v[4:5]
	v_mov_b64_e32 v[40:41], v[4:5]
	v_mov_b64_e32 v[44:45], v[4:5]
	v_mov_b64_e32 v[56:57], v[4:5]
	v_mov_b64_e32 v[60:61], v[4:5]
	v_mov_b64_e32 v[16:17], v[4:5]
	v_mov_b64_e32 v[20:21], v[4:5]
	v_mov_b64_e32 v[32:33], v[4:5]
	v_mov_b64_e32 v[36:37], v[4:5]
	v_mov_b64_e32 v[48:49], v[4:5]
	v_mov_b64_e32 v[52:53], v[4:5]
	v_mov_b64_e32 v[64:65], v[4:5]
	v_mov_b64_e32 v[68:69], v[4:5]
	v_mov_b64_e32 v[72:73], v[4:5]
	v_mov_b64_e32 v[76:77], v[4:5]
	v_mov_b64_e32 v[88:89], v[4:5]
	v_mov_b64_e32 v[92:93], v[4:5]
	v_mov_b64_e32 v[104:105], v[4:5]
	v_mov_b64_e32 v[108:109], v[4:5]
	v_mov_b64_e32 v[120:121], v[4:5]
	v_mov_b64_e32 v[124:125], v[4:5]
	v_mov_b64_e32 v[80:81], v[4:5]
	v_mov_b64_e32 v[84:85], v[4:5]
	v_mov_b64_e32 v[96:97], v[4:5]
	v_mov_b64_e32 v[100:101], v[4:5]
	v_mov_b64_e32 v[112:113], v[4:5]
	v_mov_b64_e32 v[116:117], v[4:5]
	v_mov_b64_e32 v[128:129], v[4:5]
	v_mov_b64_e32 v[132:133], v[4:5]
	s_addc_u32 s49, s61, s19
	s_add_i32 s47, s50, 0x100
	s_mov_b32 s90, 0
	v_mov_b64_e32 v[6:7], v[2:3]
	v_mov_b64_e32 v[10:11], v[2:3]
	v_mov_b64_e32 v[22:23], v[2:3]
	v_mov_b64_e32 v[26:27], v[2:3]
	v_mov_b64_e32 v[38:39], v[2:3]
	v_mov_b64_e32 v[42:43], v[2:3]
	v_mov_b64_e32 v[54:55], v[2:3]
	v_mov_b64_e32 v[58:59], v[2:3]
	v_mov_b64_e32 v[14:15], v[2:3]
	v_mov_b64_e32 v[18:19], v[2:3]
	v_mov_b64_e32 v[30:31], v[2:3]
	v_mov_b64_e32 v[34:35], v[2:3]
	v_mov_b64_e32 v[46:47], v[2:3]
	v_mov_b64_e32 v[50:51], v[2:3]
	v_mov_b64_e32 v[62:63], v[2:3]
	v_mov_b64_e32 v[66:67], v[2:3]
	v_mov_b64_e32 v[70:71], v[2:3]
	v_mov_b64_e32 v[74:75], v[2:3]
	v_mov_b64_e32 v[86:87], v[2:3]
	v_mov_b64_e32 v[90:91], v[2:3]
	v_mov_b64_e32 v[102:103], v[2:3]
	v_mov_b64_e32 v[106:107], v[2:3]
	v_mov_b64_e32 v[118:119], v[2:3]
	v_mov_b64_e32 v[122:123], v[2:3]
	v_mov_b64_e32 v[78:79], v[2:3]
	v_mov_b64_e32 v[82:83], v[2:3]
	v_mov_b64_e32 v[94:95], v[2:3]
	v_mov_b64_e32 v[98:99], v[2:3]
	v_mov_b64_e32 v[110:111], v[2:3]
	v_mov_b64_e32 v[114:115], v[2:3]
	v_mov_b64_e32 v[126:127], v[2:3]
	v_mov_b64_e32 v[130:131], v[2:3]
	s_mov_b32 s91, 0
	s_branch .LBB0_1182

.LBB0_1288:
	s_lshl_b32 s68, s67, 21
	s_andn2_b64 vcc, exec, s[36:37]
	s_lshl_b32 s69, s66, 21
	s_cbranch_vccnz .LBB0_1314
	s_and_b64 s[6:7], s[4:5], exec
	v_mov_b32_e32 v2, 0
	s_cselect_b32 s6, s68, s72
	s_cselect_b32 s7, s69, s73
	s_add_i32 s72, s72, 0x180080
	s_addk_i32 s73, 0x100
	s_mov_b32 s74, 0
	s_waitcnt lgkmcnt(0)
	v_mov_b32_e32 v3, v2
	v_mov_b64_e32 v[4:5], 0
	v_mov_b64_e32 v[6:7], 0
	v_mov_b64_e32 v[8:9], 0
	s_waitcnt vmcnt(33)
	v_mov_b64_e32 v[18:19], 0
	v_mov_b64_e32 v[20:21], 0
	s_waitcnt vmcnt(32)
	v_mov_b64_e32 v[22:23], 0
	v_mov_b64_e32 v[24:25], 0
	s_waitcnt vmcnt(29)
	v_mov_b64_e32 v[34:35], 0
	v_mov_b64_e32 v[36:37], 0
	s_waitcnt vmcnt(28)
	v_mov_b64_e32 v[38:39], 0
	v_mov_b64_e32 v[40:41], 0
	s_waitcnt vmcnt(25)
	v_mov_b64_e32 v[50:51], 0
	v_mov_b64_e32 v[52:53], 0
	s_waitcnt vmcnt(24)
	v_mov_b64_e32 v[54:55], 0
	v_mov_b64_e32 v[56:57], 0
	v_mov_b64_e32 v[10:11], 0
	v_mov_b64_e32 v[12:13], 0
	v_mov_b64_e32 v[14:15], 0
	v_mov_b64_e32 v[16:17], 0
	v_mov_b64_e32 v[26:27], 0
	v_mov_b64_e32 v[28:29], 0
	v_mov_b64_e32 v[30:31], 0
	v_mov_b64_e32 v[32:33], 0
	v_mov_b64_e32 v[42:43], 0
	v_mov_b64_e32 v[44:45], 0
	v_mov_b64_e32 v[46:47], 0
	v_mov_b64_e32 v[48:49], 0
	s_waitcnt vmcnt(23)
	v_mov_b64_e32 v[58:59], 0
	v_mov_b64_e32 v[60:61], 0
	s_waitcnt vmcnt(22)
	v_mov_b64_e32 v[62:63], 0
	v_mov_b64_e32 v[64:65], 0
	v_mov_b64_e32 v[66:67], 0
	v_mov_b64_e32 v[68:69], 0
	v_mov_b64_e32 v[70:71], 0
	v_mov_b64_e32 v[72:73], 0
	v_mov_b64_e32 v[82:83], 0
	v_mov_b64_e32 v[84:85], 0
	v_mov_b64_e32 v[86:87], 0
	v_mov_b64_e32 v[88:89], 0
	v_mov_b64_e32 v[98:99], 0
	v_mov_b64_e32 v[100:101], 0
	v_mov_b64_e32 v[102:103], 0
	v_mov_b64_e32 v[104:105], 0
	v_mov_b64_e32 v[122:123], 0
	v_mov_b64_e32 v[124:125], 0
	v_mov_b64_e32 v[126:127], 0
	v_mov_b64_e32 v[128:129], 0
	v_mov_b64_e32 v[74:75], 0
	v_mov_b64_e32 v[76:77], 0
	v_mov_b64_e32 v[78:79], 0
	v_mov_b64_e32 v[80:81], 0
	v_mov_b64_e32 v[90:91], 0
	v_mov_b64_e32 v[92:93], 0
	v_mov_b64_e32 v[94:95], 0
	v_mov_b64_e32 v[96:97], 0
	v_mov_b64_e32 v[110:111], 0
	v_mov_b64_e32 v[112:113], 0
	v_mov_b64_e32 v[114:115], 0
	v_mov_b64_e32 v[116:117], 0
	v_mov_b32_e32 v134, v2
	v_mov_b32_e32 v135, v2
	v_mov_b32_e32 v136, v2
	v_mov_b32_e32 v137, v2
	v_mov_b32_e32 v142, v2
	v_mov_b32_e32 v143, v2
	v_mov_b32_e32 v144, v2
	v_mov_b32_e32 v145, v2

.LBB0_1380:
	s_lshl_b32 s68, s67, 21
	s_andn2_b64 vcc, exec, s[40:41]
	s_lshl_b32 s69, s66, 21
	s_cbranch_vccnz .LBB0_1388
	s_and_b64 s[14:15], s[4:5], exec
	v_mov_b32_e32 v2, 0
	s_cselect_b32 s72, s68, s74
	s_cselect_b32 s73, s69, s75
	s_add_i32 s74, s74, 0x180080
	s_addk_i32 s75, 0x100
	s_mov_b32 s76, 0
	v_mov_b32_e32 v3, v2
	v_mov_b64_e32 v[4:5], 0
	s_waitcnt vmcnt(35)
	v_mov_b64_e32 v[10:11], 0
	v_mov_b64_e32 v[12:13], 0
	s_waitcnt vmcnt(33)
	v_mov_b64_e32 v[18:19], 0
	v_mov_b64_e32 v[20:21], 0
	s_waitcnt vmcnt(31)
	v_mov_b64_e32 v[26:27], 0
	v_mov_b64_e32 v[28:29], 0
	s_waitcnt vmcnt(29)
	v_mov_b64_e32 v[34:35], 0
	v_mov_b64_e32 v[36:37], 0
	s_waitcnt vmcnt(27)
	v_mov_b64_e32 v[42:43], 0
	v_mov_b64_e32 v[44:45], 0
	s_waitcnt vmcnt(25)
	v_mov_b64_e32 v[50:51], 0
	v_mov_b64_e32 v[52:53], 0
	s_waitcnt vmcnt(23)
	v_mov_b64_e32 v[58:59], 0
	v_mov_b64_e32 v[60:61], 0
	v_mov_b64_e32 v[6:7], 0
	v_mov_b64_e32 v[8:9], 0
	v_mov_b64_e32 v[14:15], 0
	v_mov_b64_e32 v[16:17], 0
	v_mov_b64_e32 v[22:23], 0
	v_mov_b64_e32 v[24:25], 0
	v_mov_b64_e32 v[30:31], 0
	v_mov_b64_e32 v[32:33], 0
	v_mov_b64_e32 v[38:39], 0
	v_mov_b64_e32 v[40:41], 0
	v_mov_b64_e32 v[46:47], 0
	v_mov_b64_e32 v[48:49], 0
	v_mov_b64_e32 v[54:55], 0
	v_mov_b64_e32 v[56:57], 0
	s_waitcnt vmcnt(22)
	v_mov_b64_e32 v[62:63], 0
	v_mov_b64_e32 v[64:65], 0
	v_mov_b64_e32 v[70:71], 0
	v_mov_b64_e32 v[72:73], 0
	v_mov_b64_e32 v[74:75], 0
	v_mov_b64_e32 v[76:77], 0
	v_mov_b64_e32 v[82:83], 0
	v_mov_b64_e32 v[84:85], 0
	v_mov_b64_e32 v[90:91], 0
	v_mov_b64_e32 v[92:93], 0
	v_mov_b64_e32 v[98:99], 0
	v_mov_b64_e32 v[100:101], 0
	v_mov_b64_e32 v[106:107], 0
	v_mov_b64_e32 v[108:109], 0
	v_mov_b64_e32 v[122:123], 0
	v_mov_b64_e32 v[124:125], 0
	v_mov_b64_e32 v[126:127], 0
	v_mov_b64_e32 v[128:129], 0
	v_mov_b64_e32 v[66:67], 0
	v_mov_b64_e32 v[68:69], 0
	v_mov_b64_e32 v[78:79], 0
	v_mov_b64_e32 v[80:81], 0
	v_mov_b64_e32 v[86:87], 0
	v_mov_b64_e32 v[88:89], 0
	v_mov_b64_e32 v[94:95], 0
	v_mov_b64_e32 v[96:97], 0
	v_mov_b64_e32 v[102:103], 0
	v_mov_b64_e32 v[104:105], 0
	v_mov_b64_e32 v[110:111], 0
	v_mov_b64_e32 v[112:113], 0
	v_mov_b64_e32 v[114:115], 0
	v_mov_b64_e32 v[116:117], 0
	v_mov_b64_e32 v[118:119], 0
	v_mov_b64_e32 v[120:121], 0

.LBB0_1400:
	s_lshl_b32 s69, s67, 21
	s_and_b64 vcc, exec, s[4:5]
	s_lshl_b32 s70, s68, 21
	s_cbranch_vccnz .LBB0_1408
	s_and_b64 s[22:23], s[6:7], exec
	v_mov_b32_e32 v2, 0
	s_cselect_b32 s73, s69, s75
	s_cselect_b32 s74, s70, s76
	s_add_i32 s75, s75, 0x180080
	s_addk_i32 s76, 0x100
	s_mov_b32 s77, 0
	v_mov_b32_e32 v3, v2
	v_mov_b64_e32 v[4:5], 0
	s_waitcnt vmcnt(35)
	v_mov_b64_e32 v[10:11], 0
	v_mov_b64_e32 v[12:13], 0
	s_waitcnt vmcnt(33)
	v_mov_b64_e32 v[18:19], 0
	v_mov_b64_e32 v[20:21], 0
	s_waitcnt vmcnt(31)
	v_mov_b64_e32 v[26:27], 0
	v_mov_b64_e32 v[28:29], 0
	s_waitcnt vmcnt(29)
	v_mov_b64_e32 v[34:35], 0
	v_mov_b64_e32 v[36:37], 0
	s_waitcnt vmcnt(27)
	v_mov_b64_e32 v[42:43], 0
	v_mov_b64_e32 v[44:45], 0
	s_waitcnt vmcnt(25)
	v_mov_b64_e32 v[50:51], 0
	v_mov_b64_e32 v[52:53], 0
	s_waitcnt vmcnt(23)
	v_mov_b64_e32 v[58:59], 0
	v_mov_b64_e32 v[60:61], 0
	v_mov_b64_e32 v[6:7], 0
	v_mov_b64_e32 v[8:9], 0
	v_mov_b64_e32 v[14:15], 0
	v_mov_b64_e32 v[16:17], 0
	v_mov_b64_e32 v[22:23], 0
	v_mov_b64_e32 v[24:25], 0
	v_mov_b64_e32 v[30:31], 0
	v_mov_b64_e32 v[32:33], 0
	v_mov_b64_e32 v[38:39], 0
	v_mov_b64_e32 v[40:41], 0
	v_mov_b64_e32 v[46:47], 0
	v_mov_b64_e32 v[48:49], 0
	v_mov_b64_e32 v[54:55], 0
	v_mov_b64_e32 v[56:57], 0
	s_waitcnt vmcnt(22)
	v_mov_b64_e32 v[62:63], 0
	v_mov_b64_e32 v[64:65], 0
	v_mov_b64_e32 v[70:71], 0
	v_mov_b64_e32 v[72:73], 0
	v_mov_b64_e32 v[74:75], 0
	v_mov_b64_e32 v[76:77], 0
	v_mov_b64_e32 v[82:83], 0
	v_mov_b64_e32 v[84:85], 0
	v_mov_b64_e32 v[90:91], 0
	v_mov_b64_e32 v[92:93], 0
	v_mov_b64_e32 v[98:99], 0
	v_mov_b64_e32 v[100:101], 0
	v_mov_b64_e32 v[106:107], 0
	v_mov_b64_e32 v[108:109], 0
	v_mov_b64_e32 v[122:123], 0
	v_mov_b64_e32 v[124:125], 0
	v_mov_b64_e32 v[126:127], 0
	v_mov_b64_e32 v[128:129], 0
	v_mov_b64_e32 v[66:67], 0
	v_mov_b64_e32 v[68:69], 0
	v_mov_b64_e32 v[78:79], 0
	v_mov_b64_e32 v[80:81], 0
	v_mov_b64_e32 v[86:87], 0
	v_mov_b64_e32 v[88:89], 0
	v_mov_b64_e32 v[94:95], 0
	v_mov_b64_e32 v[96:97], 0
	v_mov_b64_e32 v[102:103], 0
	v_mov_b64_e32 v[104:105], 0
	v_mov_b64_e32 v[110:111], 0
	v_mov_b64_e32 v[112:113], 0
	v_mov_b64_e32 v[114:115], 0
	v_mov_b64_e32 v[116:117], 0
	v_mov_b64_e32 v[118:119], 0
	v_mov_b64_e32 v[120:121], 0

.LBB0_1418:
	s_lshl_b32 s67, s65, 20
	s_and_b64 vcc, exec, s[4:5]
	s_lshl_b32 s68, s66, 20
	s_cbranch_vccnz .LBB0_1426
	s_and_b64 s[14:15], s[6:7], exec
	v_mov_b32_e32 v2, 0
	s_cselect_b32 s71, s67, s73
	s_cselect_b32 s72, s68, s74
	s_add_i32 s73, s73, 0xc0080
	s_addk_i32 s74, 0x100
	s_mov_b32 s75, 0
	v_mov_b32_e32 v3, v2
	v_mov_b64_e32 v[4:5], 0
	s_waitcnt vmcnt(35)
	v_mov_b64_e32 v[10:11], 0
	v_mov_b64_e32 v[12:13], 0
	s_waitcnt vmcnt(33)
	v_mov_b64_e32 v[18:19], 0
	v_mov_b64_e32 v[20:21], 0
	s_waitcnt vmcnt(31)
	v_mov_b64_e32 v[26:27], 0
	v_mov_b64_e32 v[28:29], 0
	s_waitcnt vmcnt(29)
	v_mov_b64_e32 v[34:35], 0
	v_mov_b64_e32 v[36:37], 0
	s_waitcnt vmcnt(27)
	v_mov_b64_e32 v[42:43], 0
	v_mov_b64_e32 v[44:45], 0
	s_waitcnt vmcnt(25)
	v_mov_b64_e32 v[50:51], 0
	v_mov_b64_e32 v[52:53], 0
	s_waitcnt vmcnt(23)
	v_mov_b64_e32 v[58:59], 0
	v_mov_b64_e32 v[60:61], 0
	v_mov_b64_e32 v[6:7], 0
	v_mov_b64_e32 v[8:9], 0
	v_mov_b64_e32 v[14:15], 0
	v_mov_b64_e32 v[16:17], 0
	v_mov_b64_e32 v[22:23], 0
	v_mov_b64_e32 v[24:25], 0
	v_mov_b64_e32 v[30:31], 0
	v_mov_b64_e32 v[32:33], 0
	v_mov_b64_e32 v[38:39], 0
	v_mov_b64_e32 v[40:41], 0
	v_mov_b64_e32 v[46:47], 0
	v_mov_b64_e32 v[48:49], 0
	v_mov_b64_e32 v[54:55], 0
	v_mov_b64_e32 v[56:57], 0
	s_waitcnt vmcnt(22)
	v_mov_b64_e32 v[62:63], 0
	v_mov_b64_e32 v[64:65], 0
	v_mov_b64_e32 v[66:67], 0
	v_mov_b64_e32 v[68:69], 0
	v_mov_b64_e32 v[74:75], 0
	v_mov_b64_e32 v[76:77], 0
	v_mov_b64_e32 v[82:83], 0
	v_mov_b64_e32 v[84:85], 0
	v_mov_b64_e32 v[90:91], 0
	v_mov_b64_e32 v[92:93], 0
	v_mov_b64_e32 v[98:99], 0
	v_mov_b64_e32 v[100:101], 0
	v_mov_b64_e32 v[106:107], 0
	v_mov_b64_e32 v[108:109], 0
	v_mov_b64_e32 v[122:123], 0
	v_mov_b64_e32 v[124:125], 0
	v_mov_b64_e32 v[126:127], 0
	v_mov_b64_e32 v[128:129], 0
	v_mov_b64_e32 v[70:71], 0
	v_mov_b64_e32 v[72:73], 0
	v_mov_b64_e32 v[78:79], 0
	v_mov_b64_e32 v[80:81], 0
	v_mov_b64_e32 v[86:87], 0
	v_mov_b64_e32 v[88:89], 0
	v_mov_b64_e32 v[94:95], 0
	v_mov_b64_e32 v[96:97], 0
	v_mov_b64_e32 v[102:103], 0
	v_mov_b64_e32 v[104:105], 0
	v_mov_b64_e32 v[110:111], 0
	v_mov_b64_e32 v[112:113], 0
	v_mov_b64_e32 v[114:115], 0
	v_mov_b64_e32 v[116:117], 0
	v_mov_b64_e32 v[118:119], 0
	v_mov_b64_e32 v[120:121], 0

.LBB0_1517:
	s_mul_i32 s76, s75, 0x560000
	s_andn2_b64 vcc, exec, s[36:37]
	s_mul_i32 s77, s74, 0x560000
	s_cbranch_vccnz .LBB0_1543
	s_and_b64 s[6:7], s[4:5], exec
	v_mov_b32_e32 v2, 0
	s_cselect_b32 s6, s76, s80
	s_cselect_b32 s7, s77, s81
	s_add_i32 s80, s80, 0x408080
	s_addk_i32 s81, 0x100
	s_mov_b32 s82, 0
	s_waitcnt lgkmcnt(0)
	v_mov_b32_e32 v3, v2
	v_mov_b64_e32 v[4:5], 0
	v_mov_b64_e32 v[6:7], 0
	v_mov_b64_e32 v[8:9], 0
	s_waitcnt vmcnt(35)
	v_mov_b64_e32 v[10:11], 0
	v_mov_b64_e32 v[12:13], 0
	s_waitcnt vmcnt(34)
	v_mov_b64_e32 v[14:15], 0
	v_mov_b64_e32 v[16:17], 0
	s_waitcnt vmcnt(32)
	v_mov_b64_e32 v[22:23], 0
	v_mov_b64_e32 v[24:25], 0
	s_waitcnt vmcnt(30)
	v_mov_b64_e32 v[30:31], 0
	v_mov_b64_e32 v[32:33], 0
	s_waitcnt vmcnt(28)
	v_mov_b64_e32 v[38:39], 0
	v_mov_b64_e32 v[40:41], 0
	s_waitcnt vmcnt(26)
	v_mov_b64_e32 v[46:47], 0
	v_mov_b64_e32 v[48:49], 0
	v_mov_b64_e32 v[18:19], 0
	v_mov_b64_e32 v[20:21], 0
	v_mov_b64_e32 v[26:27], 0
	v_mov_b64_e32 v[28:29], 0
	v_mov_b64_e32 v[34:35], 0
	v_mov_b64_e32 v[36:37], 0
	v_mov_b64_e32 v[42:43], 0
	v_mov_b64_e32 v[44:45], 0
	s_waitcnt vmcnt(25)
	v_mov_b64_e32 v[50:51], 0
	v_mov_b64_e32 v[52:53], 0
	s_waitcnt vmcnt(24)
	v_mov_b64_e32 v[54:55], 0
	v_mov_b64_e32 v[56:57], 0
	s_waitcnt vmcnt(23)
	v_mov_b64_e32 v[58:59], 0
	v_mov_b64_e32 v[60:61], 0
	s_waitcnt vmcnt(22)
	v_mov_b64_e32 v[62:63], 0
	v_mov_b64_e32 v[64:65], 0
	v_mov_b64_e32 v[66:67], 0
	v_mov_b64_e32 v[68:69], 0
	v_mov_b64_e32 v[70:71], 0
	v_mov_b64_e32 v[72:73], 0
	v_mov_b64_e32 v[74:75], 0
	v_mov_b64_e32 v[76:77], 0
	v_mov_b64_e32 v[78:79], 0
	v_mov_b64_e32 v[80:81], 0
	v_mov_b64_e32 v[86:87], 0
	v_mov_b64_e32 v[88:89], 0
	v_mov_b64_e32 v[94:95], 0
	v_mov_b64_e32 v[96:97], 0
	v_mov_b64_e32 v[102:103], 0
	v_mov_b64_e32 v[104:105], 0
	v_mov_b64_e32 v[110:111], 0
	v_mov_b64_e32 v[112:113], 0
	v_mov_b64_e32 v[82:83], 0
	v_mov_b64_e32 v[84:85], 0
	v_mov_b64_e32 v[90:91], 0
	v_mov_b64_e32 v[92:93], 0
	v_mov_b64_e32 v[98:99], 0
	v_mov_b64_e32 v[100:101], 0
	v_mov_b64_e32 v[106:107], 0
	v_mov_b64_e32 v[108:109], 0
	v_mov_b64_e32 v[114:115], 0
	v_mov_b64_e32 v[116:117], 0
	v_mov_b64_e32 v[118:119], 0
	v_mov_b64_e32 v[120:121], 0
	v_mov_b64_e32 v[122:123], 0
	v_mov_b64_e32 v[124:125], 0
	v_mov_b64_e32 v[126:127], 0
	v_mov_b64_e32 v[128:129], 0

.LBB0_1565:
	s_mul_i32 s53, s88, 0x2b0000
	s_andn2_b64 vcc, exec, s[46:47]
	s_mul_i32 s90, s89, 0x2b0000
	s_cbranch_vccnz .LBB0_1595
	s_and_b64 s[6:7], s[4:5], exec
	v_mov_b32_e32 v2, 0
	s_cselect_b32 s6, s53, s56
	s_cselect_b32 s7, s90, s55
	s_add_i32 s8, s56, 0x204080
	s_add_i32 s9, s55, 0x100
	s_mov_b32 s55, 0
	v_mov_b32_e32 v3, v2
	v_mov_b64_e32 v[4:5], 0
	v_mov_b64_e32 v[6:7], 0
	v_mov_b64_e32 v[8:9], 0
	s_waitcnt vmcnt(35)
	v_mov_b64_e32 v[10:11], 0
	v_mov_b64_e32 v[12:13], 0
	s_waitcnt vmcnt(34)
	v_mov_b64_e32 v[14:15], 0
	v_mov_b64_e32 v[16:17], 0
	s_waitcnt vmcnt(32)
	v_mov_b64_e32 v[22:23], 0
	v_mov_b64_e32 v[24:25], 0
	s_waitcnt vmcnt(30)
	v_mov_b64_e32 v[30:31], 0
	v_mov_b64_e32 v[32:33], 0
	s_waitcnt vmcnt(28)
	v_mov_b64_e32 v[38:39], 0
	v_mov_b64_e32 v[40:41], 0
	s_waitcnt vmcnt(26)
	v_mov_b64_e32 v[46:47], 0
	v_mov_b64_e32 v[48:49], 0
	v_mov_b64_e32 v[18:19], 0
	v_mov_b64_e32 v[20:21], 0
	v_mov_b64_e32 v[26:27], 0
	v_mov_b64_e32 v[28:29], 0
	v_mov_b64_e32 v[34:35], 0
	v_mov_b64_e32 v[36:37], 0
	v_mov_b64_e32 v[42:43], 0
	v_mov_b64_e32 v[44:45], 0
	s_waitcnt vmcnt(25)
	v_mov_b64_e32 v[50:51], 0
	v_mov_b64_e32 v[52:53], 0
	s_waitcnt vmcnt(24)
	v_mov_b64_e32 v[54:55], 0
	v_mov_b64_e32 v[56:57], 0
	s_waitcnt vmcnt(23)
	v_mov_b64_e32 v[58:59], 0
	v_mov_b64_e32 v[60:61], 0
	s_waitcnt vmcnt(22)
	v_mov_b64_e32 v[62:63], 0
	v_mov_b64_e32 v[64:65], 0
	v_mov_b64_e32 v[66:67], 0
	v_mov_b64_e32 v[68:69], 0
	v_mov_b64_e32 v[70:71], 0
	v_mov_b64_e32 v[72:73], 0
	v_mov_b64_e32 v[74:75], 0
	v_mov_b64_e32 v[76:77], 0
	v_mov_b64_e32 v[78:79], 0
	v_mov_b64_e32 v[80:81], 0
	v_mov_b64_e32 v[86:87], 0
	v_mov_b64_e32 v[88:89], 0
	v_mov_b64_e32 v[94:95], 0
	v_mov_b64_e32 v[96:97], 0
	v_mov_b64_e32 v[102:103], 0
	v_mov_b64_e32 v[104:105], 0
	v_mov_b64_e32 v[110:111], 0
	v_mov_b64_e32 v[112:113], 0
	v_mov_b64_e32 v[82:83], 0
	v_mov_b64_e32 v[84:85], 0
	v_mov_b64_e32 v[90:91], 0
	v_mov_b64_e32 v[92:93], 0
	v_mov_b64_e32 v[98:99], 0
	v_mov_b64_e32 v[100:101], 0
	v_mov_b64_e32 v[106:107], 0
	v_mov_b64_e32 v[108:109], 0
	v_mov_b64_e32 v[114:115], 0
	v_mov_b64_e32 v[116:117], 0
	v_mov_b64_e32 v[118:119], 0
	v_mov_b64_e32 v[120:121], 0
	v_mov_b64_e32 v[122:123], 0
	v_mov_b64_e32 v[124:125], 0
	v_mov_b64_e32 v[126:127], 0
	v_mov_b64_e32 v[128:129], 0
